# G3 epilogue second-half operands DMA'd early (counted vmcnt) + sample tile map guarded on grid 256
# speedup vs baseline: 1.0612x; 1.0138x over previous
;     __device__ __forceinline__ void operator()(const f32x4 (&acc)[2][2][4][2], const Unit& u, int wr, int wc, int fr, int fq) const {
;         const int row0 = u.pm * BM + wr * 64 + fr, col0 = u.pn * BM + wc * 32 + 4 * fq;
; #pragma unroll
;         for (int ai = 0; ai < 2; ++ai) {
;             u32x2e hw[4][2][2], pw[4][2][2]; float scv[4];
; #pragma unroll
;             for (int m = 0; m < 4; ++m) { const int row = row0 + ai * HALF + m * 16; const size_t ro = (size_t)row * 2048 + col0;
;                 scv[m] = GATE ? rss_in[row] : 0.f;
; #pragma unroll
;                 for (int bj = 0; bj < 2; ++bj)
; #pragma unroll
;                     for (int n = 0; n < 2; ++n) { const size_t p = ro + bj * HALF + n * 16; hw[m][bj][n] = *(const u32x2e*)(Hin + p); if (GATE) pw[m][bj][n] = *(const u32x2e*)(PP + p); else pw[m][bj][n] = (u32x2e){0u, 0u}; } }
.Lepi3_noalign:
	s_waitcnt vmcnt(0)
	s_barrier
	v_lshlrev_b32_e32 v130, 9, v235
	v_lshrrev_b32_e32 v131, 3, v237
	v_and_b32_e32 v132, 15, v235
	v_xor_b32_e32 v131, v131, v132
	v_lshl_add_u32 v130, v131, 4, v130
	v_bfe_u32 v131, v237, 2, 1
	v_lshl_add_u32 v130, v131, 3, v130
	v_xor_b32_e32 v131, 32, v130
	v_add_u32_e32 v132, 0x10000, v130
	v_add_u32_e32 v133, 0x10000, v131
	v_lshrrev_b32_e32 v134, 5, v216
	v_and_b32_e32 v135, 31, v216
	v_xor_b32_e32 v135, v135, v134
	v_lshlrev_b32_e32 v135, 4, v135
	v_lshl_or_b32 v134, v134, 12, v135
	v_lshrrev_b32_e32 v135, 6, v183
	s_nop 0
	v_readfirstlane_b32 s7, v135
	s_lshl_b32 s8, s4, 20
	s_lshl_b32 s9, s6, 9
	s_add_i32 s8, s8, s9
	s_lshl_b32 s9, s7, 16
	s_add_i32 s8, s8, s9
	s_lshl_b32 s7, s7, 13
	s_add_u32 s10, s46, s8
	s_addc_u32 s11, s47, 0
	s_add_u32 s14, s52, s8
	s_addc_u32 s15, s53, 0
	s_add_i32 m0, s7, 0x0
	s_add_u32 s2, s10, 0x0
	s_addc_u32 s3, s11, 0
	v_xor_b32_e32 v135, 0x0, v134
	global_load_lds_dwordx4 v135, s[2:3]
	s_add_i32 m0, s7, 0x400
	s_add_u32 s2, s10, 0x2000
	s_addc_u32 s3, s11, 0
	v_xor_b32_e32 v135, 0x20, v134
	global_load_lds_dwordx4 v135, s[2:3]
	s_add_i32 m0, s7, 0x800
	s_add_u32 s2, s10, 0x4000
	s_addc_u32 s3, s11, 0
	v_xor_b32_e32 v135, 0x40, v134
	global_load_lds_dwordx4 v135, s[2:3]
	s_add_i32 m0, s7, 0xc00
	s_add_u32 s2, s10, 0x6000
	s_addc_u32 s3, s11, 0
	v_xor_b32_e32 v135, 0x60, v134
	global_load_lds_dwordx4 v135, s[2:3]
	s_add_i32 m0, s7, 0x1000
	s_add_u32 s2, s10, 0x8000
	s_addc_u32 s3, s11, 0
	v_xor_b32_e32 v135, 0x80, v134
	global_load_lds_dwordx4 v135, s[2:3]
	s_add_i32 m0, s7, 0x1400
	s_add_u32 s2, s10, 0xa000
	s_addc_u32 s3, s11, 0
	v_xor_b32_e32 v135, 0xa0, v134
	global_load_lds_dwordx4 v135, s[2:3]
	s_add_i32 m0, s7, 0x1800
	s_add_u32 s2, s10, 0xc000
	s_addc_u32 s3, s11, 0
	v_xor_b32_e32 v135, 0xc0, v134
	global_load_lds_dwordx4 v135, s[2:3]
	s_add_i32 m0, s7, 0x1c00
	s_add_u32 s2, s10, 0xe000
	s_addc_u32 s3, s11, 0
	v_xor_b32_e32 v135, 0xe0, v134
	global_load_lds_dwordx4 v135, s[2:3]
	s_add_i32 m0, s7, 0x10000
	s_add_u32 s2, s14, 0x0
	s_addc_u32 s3, s15, 0
	v_xor_b32_e32 v135, 0x0, v134
	global_load_lds_dwordx4 v135, s[2:3]
	s_add_i32 m0, s7, 0x10400
	s_add_u32 s2, s14, 0x2000
	s_addc_u32 s3, s15, 0
	v_xor_b32_e32 v135, 0x20, v134
	global_load_lds_dwordx4 v135, s[2:3]
	s_add_i32 m0, s7, 0x10800
	s_add_u32 s2, s14, 0x4000
	s_addc_u32 s3, s15, 0
	v_xor_b32_e32 v135, 0x40, v134
	global_load_lds_dwordx4 v135, s[2:3]
	s_add_i32 m0, s7, 0x10c00
	s_add_u32 s2, s14, 0x6000
	s_addc_u32 s3, s15, 0
	v_xor_b32_e32 v135, 0x60, v134
	global_load_lds_dwordx4 v135, s[2:3]
	s_add_i32 m0, s7, 0x11000
	s_add_u32 s2, s14, 0x8000
	s_addc_u32 s3, s15, 0
	v_xor_b32_e32 v135, 0x80, v134
	global_load_lds_dwordx4 v135, s[2:3]
	s_add_i32 m0, s7, 0x11400
	s_add_u32 s2, s14, 0xa000
	s_addc_u32 s3, s15, 0
	v_xor_b32_e32 v135, 0xa0, v134
	global_load_lds_dwordx4 v135, s[2:3]
	s_add_i32 m0, s7, 0x11800
	s_add_u32 s2, s14, 0xc000
	s_addc_u32 s3, s15, 0
	v_xor_b32_e32 v135, 0xc0, v134
	global_load_lds_dwordx4 v135, s[2:3]
	s_add_i32 m0, s7, 0x11c00
	s_add_u32 s2, s14, 0xe000
	s_addc_u32 s3, s15, 0
	v_xor_b32_e32 v135, 0xe0, v134
	global_load_lds_dwordx4 v135, s[2:3]
	s_waitcnt vmcnt(0)
	s_barrier
	v_lshl_add_u32 v138, s4, 8, v235
	v_lshl_or_b32 v136, s6, 8, v237
	v_ashrrev_i32_e32 v139, 31, v138
	v_ashrrev_i32_e32 v137, 31, v136
	v_lshlrev_b64 v[140:141], 11, v[138:139]
	v_lshl_add_u64 v[142:143], v[140:141], 0, v[136:137]
	v_lshl_add_u64 v[140:141], v[138:139], 2, s[54:55]
	v_lshlrev_b64 v[142:143], 1, v[142:143]
	v_lshl_add_u64 v[144:145], s[46:47], 0, v[142:143]
	global_load_dword v250, v[140:141], off
	ds_read_b64 v[242:243], v130 offset:0
	v_lshl_add_u64 v[144:145], s[52:53], 0, v[142:143]
	v_or_b32_e32 v146, 32, v142
	v_mov_b32_e32 v147, v143
	v_or_b32_e32 v150, 0x100, v142
	v_mov_b32_e32 v151, v143
	v_lshl_add_u64 v[148:149], s[46:47], 0, v[146:147]
	v_lshl_add_u64 v[146:147], s[52:53], 0, v[146:147]
	v_lshl_add_u64 v[152:153], s[46:47], 0, v[150:151]
	ds_read_b64 v[244:245], v132 offset:0
	ds_read_b64 v[246:247], v131 offset:0
	ds_read_b64 v[248:249], v133 offset:0
	ds_read_b64 v[212:213], v130 offset:256
	v_or_b32_e32 v204, 16, v138
	v_ashrrev_i32_e32 v205, 31, v204
	v_lshlrev_b64 v[148:149], 11, v[204:205]
	v_lshl_add_u64 v[148:149], v[148:149], 0, v[136:137]
	v_lshl_add_u64 v[144:145], s[52:53], 0, v[150:151]
	v_or_b32_e32 v142, 0x120, v142
	v_lshlrev_b64 v[148:149], 1, v[148:149]
	v_lshl_add_u64 v[146:147], s[46:47], 0, v[142:143]
	v_lshl_add_u64 v[142:143], s[52:53], 0, v[142:143]
	v_lshl_add_u64 v[150:151], s[46:47], 0, v[148:149]
	ds_read_b64 v[210:211], v132 offset:256
	ds_read_b64 v[208:209], v131 offset:256
	ds_read_b64 v[206:207], v133 offset:256
	ds_read_b64 v[202:203], v130 offset:8192
	v_or_b32_e32 v144, 32, v148
	v_mov_b32_e32 v145, v149
	v_or_b32_e32 v176, 32, v138
	v_lshl_add_u64 v[142:143], s[52:53], 0, v[148:149]
	v_lshl_add_u64 v[146:147], s[46:47], 0, v[144:145]
	v_lshl_add_u64 v[144:145], s[52:53], 0, v[144:145]
	v_or_b32_e32 v150, 0x100, v148
	v_mov_b32_e32 v151, v149
	v_or_b32_e32 v148, 0x120, v148
	v_ashrrev_i32_e32 v177, 31, v176
	v_lshl_add_u64 v[152:153], s[46:47], 0, v[150:151]
	ds_read_b64 v[200:201], v132 offset:8192
	ds_read_b64 v[198:199], v131 offset:8192
	ds_read_b64 v[196:197], v133 offset:8192
	ds_read_b64 v[194:195], v130 offset:8448
	v_lshl_add_u64 v[144:145], s[46:47], 0, v[148:149]
	v_lshl_add_u64 v[146:147], s[52:53], 0, v[148:149]
	v_lshlrev_b64 v[148:149], 11, v[176:177]
	v_lshl_add_u64 v[148:149], v[148:149], 0, v[136:137]
	v_lshl_add_u64 v[142:143], s[52:53], 0, v[150:151]
	v_lshlrev_b64 v[148:149], 1, v[148:149]
;     __device__ __forceinline__ void operator()(const f32x4 (&acc)[2][2][4][2], const Unit& u, int wr, int wc, int fr, int fq) const {
;     ...
;             for (int m = 0; m < 4; ++m) { const int row = row0 + ai * HALF + m * 16; const size_t ro = (size_t)row * 2048 + col0;
;                 scv[m] = GATE ? rss_in[row] : 0.f;
; #pragma unroll
;                 for (int bj = 0; bj < 2; ++bj)
; #pragma unroll
;                     for (int n = 0; n < 2; ++n) { const size_t p = ro + bj * HALF + n * 16; hw[m][bj][n] = *(const u32x2e*)(Hin + p); if (GATE) pw[m][bj][n] = *(const u32x2e*)(PP + p); else pw[m][bj][n] = (u32x2e){0u, 0u}; } }
; #pragma unroll
;             for (int m = 0; m < 4; ++m) { const int row = row0 + ai * HALF + m * 16; const size_t ro = (size_t)row * 2048 + col0;
;                 float sc = 1.f; if (GATE) sc = rsqrtf(scv[m] * (1.f / 2048.f) + 1e-6f);
;                 float s = 0.f;
; #pragma unroll
;                 for (int bj = 0; bj < 2; ++bj)
; #pragma unroll
;                     for (int n = 0; n < 2; ++n) { const size_t p = ro + bj * HALF + n * 16; const u32x2e hh = hw[m][bj][n], pp = pw[m][bj][n]; const f32x4 a = acc[ai][bj][m][n];
	v_lshl_add_u64 v[150:151], s[46:47], 0, v[148:149]
	ds_read_b64 v[192:193], v132 offset:8448
	ds_read_b64 v[180:181], v131 offset:8448
	ds_read_b64 v[178:179], v133 offset:8448
	ds_read_b64 v[174:175], v130 offset:16384
	v_or_b32_e32 v144, 32, v148
	v_mov_b32_e32 v145, v149
	v_or_b32_e32 v158, 48, v138
	v_lshl_add_u64 v[142:143], s[52:53], 0, v[148:149]
	v_lshl_add_u64 v[146:147], s[46:47], 0, v[144:145]
	v_lshl_add_u64 v[144:145], s[52:53], 0, v[144:145]
	v_or_b32_e32 v150, 0x100, v148
	v_mov_b32_e32 v151, v149
	v_or_b32_e32 v148, 0x120, v148
	v_ashrrev_i32_e32 v159, 31, v158
	v_lshl_add_u64 v[152:153], s[46:47], 0, v[150:151]
	ds_read_b64 v[172:173], v132 offset:16384
	ds_read_b64 v[170:171], v131 offset:16384
	ds_read_b64 v[168:169], v133 offset:16384
	ds_read_b64 v[166:167], v130 offset:16640
	v_lshl_add_u64 v[144:145], s[46:47], 0, v[148:149]
	v_lshl_add_u64 v[146:147], s[52:53], 0, v[148:149]
	v_lshlrev_b64 v[148:149], 11, v[158:159]
	v_lshl_add_u64 v[148:149], v[148:149], 0, v[136:137]
	v_lshl_add_u64 v[142:143], s[52:53], 0, v[150:151]
	v_lshlrev_b64 v[226:227], 1, v[148:149]
	global_load_dword v241, v[140:141], off offset:64
	global_load_dword v240, v[140:141], off offset:128
	global_load_dword v239, v[140:141], off offset:192
	v_lshl_add_u64 v[148:149], s[46:47], 0, v[226:227]
	ds_read_b64 v[164:165], v132 offset:16640
	ds_read_b64 v[162:163], v131 offset:16640
	ds_read_b64 v[160:161], v133 offset:16640
	ds_read_b64 v[156:157], v130 offset:24576
	v_or_b32_e32 v144, 32, v226
	v_mov_b32_e32 v145, v227
	v_or_b32_e32 v222, 0x100, v226
	v_mov_b32_e32 v223, v227
	v_lshl_add_u64 v[142:143], s[52:53], 0, v[226:227]
	v_lshl_add_u64 v[146:147], s[46:47], 0, v[144:145]
	v_lshl_add_u64 v[148:149], s[46:47], 0, v[222:223]
	v_lshl_add_u64 v[144:145], s[52:53], 0, v[144:145]
	ds_read_b64 v[154:155], v132 offset:24576
	ds_read_b64 v[152:153], v131 offset:24576
	ds_read_b64 v[150:151], v133 offset:24576
	s_nop 0
	ds_read_b64 v[148:149], v130 offset:24832
	v_or_b32_e32 v226, 0x120, v226
	v_lshl_add_u64 v[142:143], s[52:53], 0, v[222:223]
	v_lshl_add_u64 v[144:145], s[46:47], 0, v[226:227]
	v_lshl_add_u64 v[222:223], s[52:53], 0, v[226:227]
	s_waitcnt vmcnt(0) lgkmcnt(0)
	v_fmamk_f32 v146, v250, 0x3a000000, v214
	v_mul_f32_e32 v147, 0x4b800000, v146
	v_cmp_gt_f32_e32 vcc, s65, v146
	v_lshlrev_b32_e32 v227, 16, v242
	v_and_b32_e32 v242, 0xffff0000, v242
	v_cndmask_b32_e32 v146, v146, v147, vcc
	v_rsq_f32_e32 v226, v146
	ds_read_b64 v[146:147], v132 offset:24832
	s_nop 0
	ds_read_b64 v[144:145], v131 offset:24832
	s_nop 0
	ds_read_b64 v[142:143], v133 offset:24832
	s_waitcnt vmcnt(0) lgkmcnt(0)
	s_barrier
	s_add_i32 m0, s7, 0x0
	s_add_u32 s2, s10, 0x80000
	s_addc_u32 s3, s11, 0
	v_xor_b32_e32 v135, 0x0, v134
	global_load_lds_dwordx4 v135, s[2:3]
	s_add_i32 m0, s7, 0x400
	s_add_u32 s2, s10, 0x82000
	s_addc_u32 s3, s11, 0
	v_xor_b32_e32 v135, 0x20, v134
	global_load_lds_dwordx4 v135, s[2:3]
	s_add_i32 m0, s7, 0x800
	s_add_u32 s2, s10, 0x84000
	s_addc_u32 s3, s11, 0
	v_xor_b32_e32 v135, 0x40, v134
	global_load_lds_dwordx4 v135, s[2:3]
	s_add_i32 m0, s7, 0xc00
	s_add_u32 s2, s10, 0x86000
	s_addc_u32 s3, s11, 0
	v_xor_b32_e32 v135, 0x60, v134
	global_load_lds_dwordx4 v135, s[2:3]
	s_add_i32 m0, s7, 0x1000
	s_add_u32 s2, s10, 0x88000
	s_addc_u32 s3, s11, 0
	v_xor_b32_e32 v135, 0x80, v134
	global_load_lds_dwordx4 v135, s[2:3]
	s_add_i32 m0, s7, 0x1400
	s_add_u32 s2, s10, 0x8a000
	s_addc_u32 s3, s11, 0
	v_xor_b32_e32 v135, 0xa0, v134
	global_load_lds_dwordx4 v135, s[2:3]
	s_add_i32 m0, s7, 0x1800
	s_add_u32 s2, s10, 0x8c000
	s_addc_u32 s3, s11, 0
	v_xor_b32_e32 v135, 0xc0, v134
	global_load_lds_dwordx4 v135, s[2:3]
	s_add_i32 m0, s7, 0x1c00
	s_add_u32 s2, s10, 0x8e000
	s_addc_u32 s3, s11, 0
	v_xor_b32_e32 v135, 0xe0, v134
	global_load_lds_dwordx4 v135, s[2:3]
	s_add_i32 m0, s7, 0x10000
	s_add_u32 s2, s14, 0x80000
	s_addc_u32 s3, s15, 0
	v_xor_b32_e32 v135, 0x0, v134
	global_load_lds_dwordx4 v135, s[2:3]
	s_add_i32 m0, s7, 0x10400
	s_add_u32 s2, s14, 0x82000
	s_addc_u32 s3, s15, 0
	v_xor_b32_e32 v135, 0x20, v134
	global_load_lds_dwordx4 v135, s[2:3]
	s_add_i32 m0, s7, 0x10800
	s_add_u32 s2, s14, 0x84000
	s_addc_u32 s3, s15, 0
	v_xor_b32_e32 v135, 0x40, v134
	global_load_lds_dwordx4 v135, s[2:3]
	s_add_i32 m0, s7, 0x10c00
	s_add_u32 s2, s14, 0x86000
	s_addc_u32 s3, s15, 0
	v_xor_b32_e32 v135, 0x60, v134
	global_load_lds_dwordx4 v135, s[2:3]
	s_add_i32 m0, s7, 0x11000
	s_add_u32 s2, s14, 0x88000
	s_addc_u32 s3, s15, 0
	v_xor_b32_e32 v135, 0x80, v134
	global_load_lds_dwordx4 v135, s[2:3]
	s_add_i32 m0, s7, 0x11400
	s_add_u32 s2, s14, 0x8a000
	s_addc_u32 s3, s15, 0
	v_xor_b32_e32 v135, 0xa0, v134
	global_load_lds_dwordx4 v135, s[2:3]
	s_add_i32 m0, s7, 0x11800
	s_add_u32 s2, s14, 0x8c000
	s_addc_u32 s3, s15, 0
	v_xor_b32_e32 v135, 0xc0, v134
	global_load_lds_dwordx4 v135, s[2:3]
	s_add_i32 m0, s7, 0x11c00
	s_add_u32 s2, s14, 0x8e000
	s_addc_u32 s3, s15, 0
	v_xor_b32_e32 v135, 0xe0, v134
	global_load_lds_dwordx4 v135, s[2:3]
	v_lshlrev_b32_e32 v225, 16, v244
	v_lshlrev_b32_e32 v250, 16, v243
	v_mul_f32_e32 v222, 0x45800000, v226
	v_cndmask_b32_e32 v226, v226, v222, vcc
	v_mul_f32_e64 v126, v126, -v226
	v_mul_f32_e32 v126, 0x3fb8aa3b, v126
	v_exp_f32_e32 v126, v126
	v_mul_f32_e64 v127, v127, -v226
	v_mul_f32_e32 v127, 0x3fb8aa3b, v127
	v_exp_f32_e32 v127, v127
	v_add_f32_e32 v126, 1.0, v126
	v_rcp_f32_e32 v126, v126
	v_mul_f32_e64 v128, v128, -v226
	v_mul_f32_e32 v128, 0x3fb8aa3b, v128
	v_mul_f32_e64 v129, v129, -v226
	v_fmac_f32_e32 v227, v126, v225
	v_add_f32_e32 v126, 1.0, v127
	v_rcp_f32_e32 v126, v126
	v_exp_f32_e32 v128, v128
; __device__ __forceinline__ unsigned cvt_pk_bf16(float lo, float hi) { unsigned r; asm volatile("v_cvt_pk_bf16_f32 %0, %1, %2" : "=v"(r) : "v"(lo), "v"(hi)); return r; }
;     __device__ __forceinline__ void operator()(const f32x4 (&acc)[2][2][4][2], const Unit& u, int wr, int wc, int fr, int fq) const {
;     ...
;             for (int m = 0; m < 4; ++m) { const int row = row0 + ai * HALF + m * 16; const size_t ro = (size_t)row * 2048 + col0;
;                 float sc = 1.f; if (GATE) sc = rsqrtf(scv[m] * (1.f / 2048.f) + 1e-6f);
;                 float s = 0.f;
; #pragma unroll
;                 for (int bj = 0; bj < 2; ++bj)
; #pragma unroll
;                     for (int n = 0; n < 2; ++n) { const size_t p = ro + bj * HALF + n * 16; const u32x2e hh = hw[m][bj][n], pp = pw[m][bj][n]; const f32x4 a = acc[ai][bj][m][n];
;                         f32x4 h; h[0] = __uint_as_float(hh.x << 16); h[1] = __uint_as_float(hh.x & 0xffff0000u); h[2] = __uint_as_float(hh.y << 16); h[3] = __uint_as_float(hh.y & 0xffff0000u);
;                         if (GATE) {
;                             h[0] += __builtin_amdgcn_rcpf(1.f + __expf(-sc * a[0])) * __uint_as_float(pp.x << 16); h[1] += __builtin_amdgcn_rcpf(1.f + __expf(-sc * a[1])) * __uint_as_float(pp.x & 0xffff0000u);
;                             h[2] += __builtin_amdgcn_rcpf(1.f + __expf(-sc * a[2])) * __uint_as_float(pp.y << 16); h[3] += __builtin_amdgcn_rcpf(1.f + __expf(-sc * a[3])) * __uint_as_float(pp.y & 0xffff0000u); }
;                         else h = h + a;
;                         s += (h[0] * h[0] + h[1] * h[1]) + (h[2] * h[2] + h[3] * h[3]);
;                         u32x2e o; o.x = cvt_pk_bf16(h[0], h[1]); o.y = cvt_pk_bf16(h[2], h[3]); *(u32x2e*)(Hout + p) = o; }
;                 s += __shfl_xor(s, 16); s += __shfl_xor(s, 32);
;                 if (fq == 0) atomicAdd(rss_out + row, s); }
	v_mul_f32_e32 v129, 0x3fb8aa3b, v129
	v_exp_f32_e32 v129, v129
	v_and_b32_e32 v127, 0xffff0000, v244
	v_fmac_f32_e32 v242, v126, v127
	v_add_f32_e32 v126, 1.0, v128
	v_mul_f32_e64 v122, v122, -v226
	v_rcp_f32_e32 v126, v126
	v_add_f32_e32 v127, 1.0, v129
	v_mul_f32_e32 v122, 0x3fb8aa3b, v122
	v_rcp_f32_e32 v127, v127
	v_exp_f32_e32 v122, v122
	v_lshlrev_b32_e32 v128, 16, v245
	v_and_b32_e32 v243, 0xffff0000, v243
	v_fmac_f32_e32 v250, v126, v128
	v_and_b32_e32 v126, 0xffff0000, v245
	v_mul_f32_e64 v123, v123, -v226
	v_fmac_f32_e32 v243, v127, v126
	v_add_f32_e32 v122, 1.0, v122
	v_mul_f32_e32 v123, 0x3fb8aa3b, v123
	v_lshlrev_b64 v[222:223], 12, v[138:139]
	v_mul_f32_e32 v126, v242, v242
	v_mul_f32_e32 v127, v243, v243
	v_rcp_f32_e32 v122, v122
	v_exp_f32_e32 v123, v123
	v_fmac_f32_e32 v126, v227, v227
	v_fmac_f32_e32 v127, v250, v250
	v_lshl_add_u64 v[128:129], s[48:49], 0, v[222:223]
	v_add_f32_e32 v225, v126, v127
	v_cvt_pk_bf16_f32 v126, v227, v242
	v_lshl_add_u64 v[128:129], v[136:137], 1, v[128:129]
	v_cvt_pk_bf16_f32 v127, v250, v243
	global_store_dwordx2 v[128:129], v[126:127], off
	v_lshlrev_b32_e32 v126, 16, v246
	v_lshlrev_b32_e32 v227, 16, v248
	v_mul_f32_e64 v124, v124, -v226
	v_fmac_f32_e32 v126, v122, v227
	v_add_f32_e32 v122, 1.0, v123
	v_mul_f32_e32 v124, 0x3fb8aa3b, v124
	v_mul_f32_e64 v125, v125, -v226
	v_rcp_f32_e32 v122, v122
	v_exp_f32_e32 v124, v124
	v_mul_f32_e32 v125, 0x3fb8aa3b, v125
	v_exp_f32_e32 v125, v125
	v_and_b32_e32 v127, 0xffff0000, v246
	v_and_b32_e32 v123, 0xffff0000, v248
	v_fmac_f32_e32 v127, v122, v123
	v_add_f32_e32 v122, 1.0, v124
	v_mul_f32_e64 v118, v118, -v226
	v_rcp_f32_e32 v122, v122
	v_add_f32_e32 v123, 1.0, v125
	v_mul_f32_e32 v118, 0x3fb8aa3b, v118
	v_rcp_f32_e32 v123, v123
	v_exp_f32_e32 v118, v118
	v_lshlrev_b32_e32 v222, 16, v247
	v_lshlrev_b32_e32 v124, 16, v249
	v_and_b32_e32 v223, 0xffff0000, v247
	v_fmac_f32_e32 v222, v122, v124
	v_and_b32_e32 v122, 0xffff0000, v249
	v_mul_f32_e64 v119, v119, -v226
	v_fmac_f32_e32 v223, v123, v122
	v_add_f32_e32 v118, 1.0, v118
	v_mul_f32_e32 v119, 0x3fb8aa3b, v119
	v_mul_f32_e32 v122, v127, v127
	v_mul_f32_e32 v123, v223, v223
	v_rcp_f32_e32 v118, v118
	v_exp_f32_e32 v119, v119
	v_fmac_f32_e32 v122, v126, v126
	v_fmac_f32_e32 v123, v222, v222
	v_add_f32_e32 v122, v122, v123
	v_add_f32_e32 v124, v225, v122
	v_cvt_pk_bf16_f32 v122, v126, v127
	v_lshlrev_b32_e32 v125, 16, v212
	v_and_b32_e32 v126, 0xffff0000, v212
	v_lshlrev_b32_e32 v127, 16, v213
	v_and_b32_e32 v212, 0xffff0000, v213
	v_lshlrev_b32_e32 v213, 16, v210
	v_mul_f32_e64 v120, v120, -v226
	v_fmac_f32_e32 v125, v118, v213
	v_add_f32_e32 v118, 1.0, v119
	v_mul_f32_e32 v120, 0x3fb8aa3b, v120
	v_mul_f32_e64 v121, v121, -v226
	v_rcp_f32_e32 v118, v118
	v_exp_f32_e32 v120, v120
	v_mul_f32_e32 v121, 0x3fb8aa3b, v121
	v_exp_f32_e32 v121, v121
	v_and_b32_e32 v119, 0xffff0000, v210
	v_mul_f32_e64 v114, v114, -v226
	v_fmac_f32_e32 v126, v118, v119
	v_add_f32_e32 v118, 1.0, v120
	v_mul_f32_e32 v114, 0x3fb8aa3b, v114
	v_rcp_f32_e32 v118, v118
	v_add_f32_e32 v119, 1.0, v121
	v_exp_f32_e32 v114, v114
	v_rcp_f32_e32 v119, v119
	v_lshlrev_b32_e32 v120, 16, v211
	v_mul_f32_e64 v115, v115, -v226
	v_fmac_f32_e32 v127, v118, v120
	v_and_b32_e32 v118, 0xffff0000, v211
	v_add_f32_e32 v114, 1.0, v114
	v_mul_f32_e32 v115, 0x3fb8aa3b, v115
	v_fmac_f32_e32 v212, v119, v118
	v_rcp_f32_e32 v114, v114
	v_exp_f32_e32 v115, v115
	v_mul_f32_e32 v118, v126, v126
	v_mul_f32_e32 v119, v212, v212
	v_fmac_f32_e32 v118, v125, v125
	v_fmac_f32_e32 v119, v127, v127
	v_add_f32_e32 v118, v118, v119
	v_lshlrev_b32_e32 v119, 16, v208
	v_and_b32_e32 v120, 0xffff0000, v208
	v_lshlrev_b32_e32 v208, 16, v206
	v_mul_f32_e64 v116, v116, -v226
	v_fmac_f32_e32 v119, v114, v208
	v_add_f32_e32 v114, 1.0, v115
	v_mul_f32_e32 v116, 0x3fb8aa3b, v116
	v_mul_f32_e64 v117, v117, -v226
	v_rcp_f32_e32 v114, v114
	v_exp_f32_e32 v116, v116
	v_mul_f32_e32 v117, 0x3fb8aa3b, v117
	v_exp_f32_e32 v117, v117
	v_and_b32_e32 v115, 0xffff0000, v206
	v_fmac_f32_e32 v120, v114, v115
	v_add_f32_e32 v114, 1.0, v116
	v_rcp_f32_e32 v114, v114
	v_add_f32_e32 v115, 1.0, v117
	v_rcp_f32_e32 v115, v115
	v_lshlrev_b32_e32 v121, 16, v209
	v_lshlrev_b32_e32 v116, 16, v207
	v_add_f32_e32 v118, v118, v124
	v_and_b32_e32 v124, 0xffff0000, v209
	v_fmac_f32_e32 v121, v114, v116
	v_and_b32_e32 v114, 0xffff0000, v207
	v_fmac_f32_e32 v124, v115, v114
	v_mul_f32_e32 v114, v120, v120
	v_mul_f32_e32 v115, v124, v124
	v_fmac_f32_e32 v114, v119, v119
	v_fmac_f32_e32 v115, v121, v121
	v_add_f32_e32 v114, v114, v115
	v_and_b32_e32 v115, 64, v216
	v_add_f32_e32 v116, v114, v118
	v_xor_b32_e32 v114, 16, v216
	v_add_u32_e32 v117, 64, v115
	v_cmp_lt_i32_e32 vcc, v114, v117
	v_cvt_pk_bf16_f32 v123, v222, v223
	global_store_dwordx2 v[128:129], v[122:123], off offset:32
	s_nop 0
	v_cndmask_b32_e32 v114, v216, v114, vcc
	v_lshlrev_b32_e32 v206, 2, v114
	ds_bpermute_b32 v118, v206, v116
	v_cvt_pk_bf16_f32 v114, v125, v126
	v_cvt_pk_bf16_f32 v115, v127, v212
	global_store_dwordx2 v[128:129], v[114:115], off offset:256
	v_xor_b32_e32 v114, 32, v216
	v_cmp_lt_i32_e32 vcc, v114, v117
	s_waitcnt lgkmcnt(0)
	v_add_f32_e32 v116, v116, v118
	v_cndmask_b32_e32 v114, v216, v114, vcc
	v_lshlrev_b32_e32 v207, 2, v114
	ds_bpermute_b32 v117, v207, v116
	v_cvt_pk_bf16_f32 v114, v119, v120
	v_cvt_pk_bf16_f32 v115, v121, v124
	global_store_dwordx2 v[128:129], v[114:115], off offset:288
	v_lshl_add_u64 v[114:115], v[138:139], 2, s[50:51]
	s_and_saveexec_b64 s[0:1], s[42:43]
	s_cbranch_execz .LBB0_47
	s_waitcnt lgkmcnt(0)
	v_add_f32_e32 v116, v116, v117
	global_atomic_add_f32 v[114:115], v116, off

;     __device__ __forceinline__ void operator()(const f32x4 (&acc)[2][2][4][2], const Unit& u, int wr, int wc, int fr, int fq) const {
;     ...
;         for (int ai = 0; ai < 2; ++ai) {
;             u32x2e hw[4][2][2], pw[4][2][2]; float scv[4];
; #pragma unroll
;             for (int m = 0; m < 4; ++m) { const int row = row0 + ai * HALF + m * 16; const size_t ro = (size_t)row * 2048 + col0;
;                 scv[m] = GATE ? rss_in[row] : 0.f;
; #pragma unroll
;                 for (int bj = 0; bj < 2; ++bj)
; #pragma unroll
;                     for (int n = 0; n < 2; ++n) { const size_t p = ro + bj * HALF + n * 16; hw[m][bj][n] = *(const u32x2e*)(Hin + p); if (GATE) pw[m][bj][n] = *(const u32x2e*)(PP + p); else pw[m][bj][n] = (u32x2e){0u, 0u}; } }
; #pragma unroll
;             for (int m = 0; m < 4; ++m) { const int row = row0 + ai * HALF + m * 16; const size_t ro = (size_t)row * 2048 + col0;
;                 float sc = 1.f; if (GATE) sc = rsqrtf(scv[m] * (1.f / 2048.f) + 1e-6f);
.LBB0_53:
	s_or_b64 exec, exec, s[0:1]
	s_waitcnt vmcnt(16)
	s_barrier
	v_add_u32_e32 v144, 0x80, v138
	v_ashrrev_i32_e32 v145, 31, v144
	s_waitcnt lgkmcnt(0)
	v_lshlrev_b64 v[66:67], 11, v[144:145]
	v_lshl_add_u64 v[66:67], v[66:67], 0, v[136:137]
	v_lshlrev_b64 v[66:67], 1, v[66:67]
	v_lshl_add_u64 v[68:69], s[46:47], 0, v[66:67]
	global_load_dword v143, v[140:141], off offset:512
	ds_read_b64 v[146:147], v130 offset:0
	v_lshl_add_u64 v[68:69], s[52:53], 0, v[66:67]
	v_or_b32_e32 v70, 32, v66
	v_mov_b32_e32 v71, v67
	v_or_b32_e32 v74, 0x100, v66
	v_mov_b32_e32 v75, v67
	v_lshl_add_u64 v[72:73], s[46:47], 0, v[70:71]
	v_lshl_add_u64 v[70:71], s[52:53], 0, v[70:71]
	v_lshl_add_u64 v[76:77], s[46:47], 0, v[74:75]
	ds_read_b64 v[148:149], v132 offset:0
	ds_read_b64 v[150:151], v131 offset:0
	ds_read_b64 v[152:153], v133 offset:0
	ds_read_b64 v[128:129], v130 offset:256
	v_add_u32_e32 v120, 0x90, v138
	v_ashrrev_i32_e32 v121, 31, v120
	v_lshlrev_b64 v[72:73], 11, v[120:121]
	v_lshl_add_u64 v[72:73], v[72:73], 0, v[136:137]
	v_lshl_add_u64 v[68:69], s[52:53], 0, v[74:75]
	v_or_b32_e32 v66, 0x120, v66
	v_lshlrev_b64 v[72:73], 1, v[72:73]
	v_lshl_add_u64 v[70:71], s[46:47], 0, v[66:67]
	v_lshl_add_u64 v[66:67], s[52:53], 0, v[66:67]
	v_lshl_add_u64 v[74:75], s[46:47], 0, v[72:73]
	ds_read_b64 v[126:127], v132 offset:256
	ds_read_b64 v[124:125], v131 offset:256
	ds_read_b64 v[122:123], v133 offset:256
	ds_read_b64 v[118:119], v130 offset:8192
	v_or_b32_e32 v68, 32, v72
	v_mov_b32_e32 v69, v73
	v_add_u32_e32 v100, 0xa0, v138
	v_lshl_add_u64 v[66:67], s[52:53], 0, v[72:73]
	v_lshl_add_u64 v[70:71], s[46:47], 0, v[68:69]
	v_lshl_add_u64 v[68:69], s[52:53], 0, v[68:69]
	v_or_b32_e32 v74, 0x100, v72
	v_mov_b32_e32 v75, v73
	v_or_b32_e32 v72, 0x120, v72
	v_ashrrev_i32_e32 v101, 31, v100
	v_lshl_add_u64 v[76:77], s[46:47], 0, v[74:75]
	ds_read_b64 v[116:117], v132 offset:8192
	ds_read_b64 v[112:113], v131 offset:8192
	ds_read_b64 v[110:111], v133 offset:8192
	ds_read_b64 v[108:109], v130 offset:8448
	v_lshl_add_u64 v[68:69], s[46:47], 0, v[72:73]
	v_lshl_add_u64 v[70:71], s[52:53], 0, v[72:73]
	v_lshlrev_b64 v[72:73], 11, v[100:101]
	v_lshl_add_u64 v[72:73], v[72:73], 0, v[136:137]
	v_lshl_add_u64 v[66:67], s[52:53], 0, v[74:75]
	v_lshlrev_b64 v[72:73], 1, v[72:73]
	v_lshl_add_u64 v[74:75], s[46:47], 0, v[72:73]
	ds_read_b64 v[106:107], v132 offset:8448
	ds_read_b64 v[104:105], v131 offset:8448
	ds_read_b64 v[102:103], v133 offset:8448
	ds_read_b64 v[98:99], v130 offset:16384
	v_or_b32_e32 v68, 32, v72
	v_mov_b32_e32 v69, v73
	v_add_u32_e32 v82, 0xb0, v138
	v_lshl_add_u64 v[66:67], s[52:53], 0, v[72:73]
	v_lshl_add_u64 v[70:71], s[46:47], 0, v[68:69]
	v_lshl_add_u64 v[68:69], s[52:53], 0, v[68:69]
	v_or_b32_e32 v74, 0x100, v72
	v_mov_b32_e32 v75, v73
	v_or_b32_e32 v72, 0x120, v72
	v_ashrrev_i32_e32 v83, 31, v82
	v_lshl_add_u64 v[76:77], s[46:47], 0, v[74:75]
	ds_read_b64 v[96:97], v132 offset:16384
	ds_read_b64 v[94:95], v131 offset:16384
	ds_read_b64 v[92:93], v133 offset:16384
	ds_read_b64 v[90:91], v130 offset:16640
	v_lshl_add_u64 v[68:69], s[46:47], 0, v[72:73]
	v_lshl_add_u64 v[70:71], s[52:53], 0, v[72:73]
	v_lshlrev_b64 v[72:73], 11, v[82:83]
	v_lshl_add_u64 v[72:73], v[72:73], 0, v[136:137]
	v_lshl_add_u64 v[66:67], s[52:53], 0, v[74:75]
	global_load_dword v142, v[140:141], off offset:576
	global_load_dword v139, v[140:141], off offset:640
	global_load_dword v138, v[140:141], off offset:704
	v_lshlrev_b64 v[140:141], 1, v[72:73]
	v_lshl_add_u64 v[72:73], s[46:47], 0, v[140:141]
	ds_read_b64 v[88:89], v132 offset:16640
	ds_read_b64 v[86:87], v131 offset:16640
	ds_read_b64 v[84:85], v133 offset:16640
	ds_read_b64 v[80:81], v130 offset:24576
	v_or_b32_e32 v68, 32, v140
	v_mov_b32_e32 v69, v141
	v_or_b32_e32 v154, 0x100, v140
	v_mov_b32_e32 v155, v141
	v_lshl_add_u64 v[66:67], s[52:53], 0, v[140:141]
	v_lshl_add_u64 v[70:71], s[46:47], 0, v[68:69]
	v_lshl_add_u64 v[72:73], s[46:47], 0, v[154:155]
	v_lshl_add_u64 v[68:69], s[52:53], 0, v[68:69]
	ds_read_b64 v[78:79], v132 offset:24576
	ds_read_b64 v[76:77], v131 offset:24576
	ds_read_b64 v[74:75], v133 offset:24576
	s_nop 0
	ds_read_b64 v[72:73], v130 offset:24832
	v_or_b32_e32 v140, 0x120, v140
	v_lshl_add_u64 v[66:67], s[52:53], 0, v[154:155]
	v_lshl_add_u64 v[68:69], s[46:47], 0, v[140:141]
	v_lshl_add_u64 v[140:141], s[52:53], 0, v[140:141]
	s_waitcnt vmcnt(0) lgkmcnt(0)
	v_fmamk_f32 v70, v143, 0x3a000000, v214
	v_mul_f32_e32 v71, 0x4b800000, v70
	v_cmp_gt_f32_e32 vcc, s65, v70
	s_waitcnt vmcnt(0) lgkmcnt(0)
	v_lshlrev_b32_e32 v154, 16, v148
	v_cndmask_b32_e32 v70, v70, v71, vcc
	v_rsq_f32_e32 v143, v70
	ds_read_b64 v[70:71], v132 offset:24832
	s_nop 0
	ds_read_b64 v[68:69], v131 offset:24832
	s_nop 0
	ds_read_b64 v[66:67], v133 offset:24832
	s_waitcnt vmcnt(0) lgkmcnt(0)
; __device__ __forceinline__ unsigned cvt_pk_bf16(float lo, float hi) { unsigned r; asm volatile("v_cvt_pk_bf16_f32 %0, %1, %2" : "=v"(r) : "v"(lo), "v"(hi)); return r; }
;     __device__ __forceinline__ void operator()(const f32x4 (&acc)[2][2][4][2], const Unit& u, int wr, int wc, int fr, int fq) const {
;     ...
;             for (int m = 0; m < 4; ++m) { const int row = row0 + ai * HALF + m * 16; const size_t ro = (size_t)row * 2048 + col0;
;                 float sc = 1.f; if (GATE) sc = rsqrtf(scv[m] * (1.f / 2048.f) + 1e-6f);
;                 float s = 0.f;
; #pragma unroll
;                 for (int bj = 0; bj < 2; ++bj)
; #pragma unroll
;                     for (int n = 0; n < 2; ++n) { const size_t p = ro + bj * HALF + n * 16; const u32x2e hh = hw[m][bj][n], pp = pw[m][bj][n]; const f32x4 a = acc[ai][bj][m][n];
;                         f32x4 h; h[0] = __uint_as_float(hh.x << 16); h[1] = __uint_as_float(hh.x & 0xffff0000u); h[2] = __uint_as_float(hh.y << 16); h[3] = __uint_as_float(hh.y & 0xffff0000u);
;                         if (GATE) {
;                             h[0] += __builtin_amdgcn_rcpf(1.f + __expf(-sc * a[0])) * __uint_as_float(pp.x << 16); h[1] += __builtin_amdgcn_rcpf(1.f + __expf(-sc * a[1])) * __uint_as_float(pp.x & 0xffff0000u);
;                             h[2] += __builtin_amdgcn_rcpf(1.f + __expf(-sc * a[2])) * __uint_as_float(pp.y << 16); h[3] += __builtin_amdgcn_rcpf(1.f + __expf(-sc * a[3])) * __uint_as_float(pp.y & 0xffff0000u); }
;                         else h = h + a;
;                         s += (h[0] * h[0] + h[1] * h[1]) + (h[2] * h[2] + h[3] * h[3]);
;                         u32x2e o; o.x = cvt_pk_bf16(h[0], h[1]); o.y = cvt_pk_bf16(h[2], h[3]); *(u32x2e*)(Hout + p) = o; }
;                 s += __shfl_xor(s, 16); s += __shfl_xor(s, 32);
;                 if (fq == 0) atomicAdd(rss_out + row, s); }
	v_mul_f32_e32 v140, 0x45800000, v143
	v_cndmask_b32_e32 v143, v143, v140, vcc
	v_mul_f32_e64 v62, v62, -v143
	v_mul_f32_e32 v62, 0x3fb8aa3b, v62
	v_exp_f32_e32 v62, v62
	v_mul_f32_e64 v63, v63, -v143
	v_mul_f32_e32 v63, 0x3fb8aa3b, v63
	v_exp_f32_e32 v63, v63
	v_add_f32_e32 v62, 1.0, v62
	v_rcp_f32_e32 v62, v62
	v_lshlrev_b64 v[140:141], 12, v[144:145]
	v_lshlrev_b32_e32 v144, 16, v146
	v_mul_f32_e64 v64, v64, -v143
	v_fmac_f32_e32 v144, v62, v154
	v_add_f32_e32 v62, 1.0, v63
	v_mul_f32_e32 v64, 0x3fb8aa3b, v64
	v_mul_f32_e64 v65, v65, -v143
	v_rcp_f32_e32 v62, v62
	v_exp_f32_e32 v64, v64
	v_mul_f32_e32 v65, 0x3fb8aa3b, v65
	v_exp_f32_e32 v65, v65
	v_and_b32_e32 v145, 0xffff0000, v146
	v_and_b32_e32 v63, 0xffff0000, v148
	v_fmac_f32_e32 v145, v62, v63
	v_add_f32_e32 v62, 1.0, v64
	v_mul_f32_e64 v58, v58, -v143
	v_rcp_f32_e32 v62, v62
	v_add_f32_e32 v63, 1.0, v65
	v_mul_f32_e32 v58, 0x3fb8aa3b, v58
	v_rcp_f32_e32 v63, v63
	v_exp_f32_e32 v58, v58
	v_lshlrev_b32_e32 v146, 16, v147
	v_lshlrev_b32_e32 v64, 16, v149
	v_and_b32_e32 v147, 0xffff0000, v147
	v_fmac_f32_e32 v146, v62, v64
	v_and_b32_e32 v62, 0xffff0000, v149
	v_mul_f32_e64 v59, v59, -v143
	v_fmac_f32_e32 v147, v63, v62
	v_add_f32_e32 v58, 1.0, v58
	v_mul_f32_e32 v59, 0x3fb8aa3b, v59
	v_mul_f32_e32 v62, v145, v145
	v_mul_f32_e32 v63, v147, v147
	v_rcp_f32_e32 v58, v58
	v_exp_f32_e32 v59, v59
	v_fmac_f32_e32 v62, v144, v144
	v_fmac_f32_e32 v63, v146, v146
	v_lshl_add_u64 v[64:65], s[48:49], 0, v[140:141]
	v_add_f32_e32 v148, v62, v63
	v_cvt_pk_bf16_f32 v62, v144, v145
	v_lshl_add_u64 v[64:65], v[136:137], 1, v[64:65]
	v_cvt_pk_bf16_f32 v63, v146, v147
	global_store_dwordx2 v[64:65], v[62:63], off
	s_waitcnt vmcnt(33)
	v_lshlrev_b32_e32 v62, 16, v150
	s_waitcnt vmcnt(32)
	v_lshlrev_b32_e32 v144, 16, v152
	v_mul_f32_e64 v60, v60, -v143
	v_fmac_f32_e32 v62, v58, v144
	v_add_f32_e32 v58, 1.0, v59
	v_mul_f32_e32 v60, 0x3fb8aa3b, v60
	v_mul_f32_e64 v54, v54, -v143
	v_rcp_f32_e32 v58, v58
	v_exp_f32_e32 v60, v60
	v_mul_f32_e32 v54, 0x3fb8aa3b, v54
	v_exp_f32_e32 v54, v54
	v_and_b32_e32 v63, 0xffff0000, v150
	v_and_b32_e32 v59, 0xffff0000, v152
	v_mul_f32_e64 v61, v61, -v143
	v_mul_f32_e32 v61, 0x3fb8aa3b, v61
	v_fmac_f32_e32 v63, v58, v59
	v_add_f32_e32 v58, 1.0, v60
	v_mul_f32_e64 v55, v55, -v143
	v_exp_f32_e32 v61, v61
	v_rcp_f32_e32 v58, v58
	v_add_f32_e32 v54, 1.0, v54
	v_mul_f32_e32 v55, 0x3fb8aa3b, v55
	v_rcp_f32_e32 v54, v54
	v_exp_f32_e32 v55, v55
	v_lshlrev_b32_e32 v140, 16, v151
	v_lshlrev_b32_e32 v60, 16, v153
	v_add_f32_e32 v59, 1.0, v61
	v_fmac_f32_e32 v140, v58, v60
	s_waitcnt vmcnt(31)
	v_lshlrev_b32_e32 v60, 16, v128
	v_and_b32_e32 v61, 0xffff0000, v128
	s_waitcnt vmcnt(30)
	v_lshlrev_b32_e32 v128, 16, v126
	v_mul_f32_e64 v56, v56, -v143
	v_fmac_f32_e32 v60, v54, v128
	v_add_f32_e32 v54, 1.0, v55
	v_mul_f32_e32 v56, 0x3fb8aa3b, v56
	v_mul_f32_e64 v57, v57, -v143
	v_rcp_f32_e32 v59, v59
	v_rcp_f32_e32 v54, v54
	v_exp_f32_e32 v56, v56
	v_mul_f32_e32 v57, 0x3fb8aa3b, v57
	v_exp_f32_e32 v57, v57
	v_and_b32_e32 v141, 0xffff0000, v151
	v_and_b32_e32 v58, 0xffff0000, v153
	v_and_b32_e32 v55, 0xffff0000, v126
	v_fmac_f32_e32 v141, v59, v58
	v_fmac_f32_e32 v61, v54, v55
	v_add_f32_e32 v54, 1.0, v56
	v_mul_f32_e64 v50, v50, -v143
	v_mul_f32_e32 v58, v63, v63
	v_mul_f32_e32 v59, v141, v141
	v_rcp_f32_e32 v54, v54
	v_add_f32_e32 v55, 1.0, v57
	v_mul_f32_e32 v50, 0x3fb8aa3b, v50
	v_fmac_f32_e32 v58, v62, v62
	v_fmac_f32_e32 v59, v140, v140
	v_rcp_f32_e32 v55, v55
	v_exp_f32_e32 v50, v50
	v_add_f32_e32 v58, v58, v59
	v_add_f32_e32 v59, v148, v58
	v_cvt_pk_bf16_f32 v58, v62, v63
	v_lshlrev_b32_e32 v62, 16, v129
	v_lshlrev_b32_e32 v56, 16, v127
	v_and_b32_e32 v63, 0xffff0000, v129
	v_fmac_f32_e32 v62, v54, v56
	v_and_b32_e32 v54, 0xffff0000, v127
	v_mul_f32_e64 v51, v51, -v143
	v_fmac_f32_e32 v63, v55, v54
	v_add_f32_e32 v50, 1.0, v50
	v_mul_f32_e32 v51, 0x3fb8aa3b, v51
	v_mul_f32_e32 v54, v61, v61
	v_mul_f32_e32 v55, v63, v63
	v_rcp_f32_e32 v50, v50
	v_exp_f32_e32 v51, v51
	v_fmac_f32_e32 v54, v60, v60
	v_fmac_f32_e32 v55, v62, v62
	v_add_f32_e32 v54, v54, v55
	v_add_f32_e32 v54, v54, v59
	s_waitcnt vmcnt(29)
	v_lshlrev_b32_e32 v55, 16, v124
	s_waitcnt vmcnt(28)
	v_lshlrev_b32_e32 v59, 16, v122
	v_mul_f32_e64 v52, v52, -v143
	v_fmac_f32_e32 v55, v50, v59
	v_add_f32_e32 v50, 1.0, v51
	v_mul_f32_e32 v52, 0x3fb8aa3b, v52
	v_mul_f32_e64 v53, v53, -v143
	v_rcp_f32_e32 v50, v50
	v_exp_f32_e32 v52, v52
	v_mul_f32_e32 v53, 0x3fb8aa3b, v53
	v_exp_f32_e32 v53, v53
	v_and_b32_e32 v56, 0xffff0000, v124
	v_and_b32_e32 v51, 0xffff0000, v122
	v_fmac_f32_e32 v56, v50, v51
	v_add_f32_e32 v50, 1.0, v52
	v_rcp_f32_e32 v50, v50
	v_add_f32_e32 v51, 1.0, v53
	v_rcp_f32_e32 v51, v51
	v_lshlrev_b32_e32 v57, 16, v125
	v_lshlrev_b32_e32 v52, 16, v123
	v_and_b32_e32 v124, 0xffff0000, v125
	v_fmac_f32_e32 v57, v50, v52
	v_and_b32_e32 v50, 0xffff0000, v123
	v_fmac_f32_e32 v124, v51, v50
	v_mul_f32_e32 v50, v56, v56
	v_mul_f32_e32 v51, v124, v124
	v_fmac_f32_e32 v50, v55, v55
	v_fmac_f32_e32 v51, v57, v57
	v_add_f32_e32 v50, v50, v51
	v_add_f32_e32 v50, v50, v54
	ds_bpermute_b32 v51, v206, v50
	v_cvt_pk_bf16_f32 v59, v140, v141
	global_store_dwordx2 v[64:65], v[58:59], off offset:32
	v_cvt_pk_bf16_f32 v52, v60, v61
	v_cvt_pk_bf16_f32 v53, v62, v63
	s_waitcnt lgkmcnt(0)
	v_add_f32_e32 v50, v50, v51
	ds_bpermute_b32 v51, v207, v50
	global_store_dwordx2 v[64:65], v[52:53], off offset:256
	v_cvt_pk_bf16_f32 v52, v55, v56
	v_cvt_pk_bf16_f32 v53, v57, v124
	global_store_dwordx2 v[64:65], v[52:53], off offset:288
	s_and_saveexec_b64 s[0:1], s[42:43]
	s_cbranch_execz .LBB0_55
	s_waitcnt lgkmcnt(0)
	v_add_f32_e32 v50, v50, v51
	global_atomic_add_f32 v[114:115], v50, off offset:512

; template <bool GATE>
; __device__ __forceinline__ void sample_gemm_res(LAS unsigned char* lds, const bf16* Amat, const bf16* Bt, const bf16* Hin, bf16* Hout, float* rss_out, const bf16* PP, const float* rss_in, int bid, int tid) {
;     const int wave = tid >> 6, lane = tid & 63, lr = lane & 15, kg = lane >> 4;
;   for (int tile = bid; tile < 256; tile += (int)gridDim.x) {
;     const int m0 = TP + (tile & 7) * 64, n0 = (tile >> 3) * 64;
;     const bf16x8* ap = (const bf16x8*)(Amat + (size_t)(m0 + lr) * 2048 + wave * 256 + 8 * kg);
;     const bf16x8* bp = (const bf16x8*)(Bt + (size_t)(n0 + lr) * 2048 + wave * 256 + 8 * kg);
;     const int erow = m0 + (tid >> 3); const size_t ep = (size_t)erow * 2048 + n0 + (tid & 7) * 8;
.LBB0_64:
	v_mov_b32_e32 v0, v183
	s_and_b64 vcc, exec, s[40:41]
	s_cbranch_vccnz .LBB0_71
	v_and_b32_e32 v8, 64, v216
	v_xor_b32_e32 v7, 1, v216
	v_add_u32_e32 v8, 64, v8
	v_cmp_lt_i32_e32 vcc, v7, v8
	s_waitcnt vmcnt(0)
	v_and_b32_e32 v75, 15, v0
	v_bfe_u32 v4, v0, 4, 2
	v_cndmask_b32_e32 v7, v216, v7, vcc
	v_lshlrev_b32_e32 v90, 2, v7
	v_xor_b32_e32 v7, 2, v216
	v_lshlrev_b32_e32 v2, 2, v0
	v_ashrrev_i32_e32 v88, 3, v0
	v_and_b32_e32 v5, 7, v0
	v_and_b32_e32 v0, 0x3fffffc0, v0
	v_cmp_lt_i32_e32 vcc, v7, v8
	v_lshl_or_b32 v0, v4, 2, v0
	s_load_dwordx2 s[0:1], s[60:61], 0x148
	v_cndmask_b32_e32 v7, v216, v7, vcc
	v_and_b32_e32 v2, 0xffffff00, v2
	v_lshlrev_b32_e32 v6, 2, v75
	v_lshlrev_b32_e32 v91, 2, v7
	v_xor_b32_e32 v7, 4, v216
	v_mul_lo_u32 v0, v0, s30
	s_waitcnt lgkmcnt(0)
	v_ashrrev_i32_e32 v3, 31, v2
	v_cmp_lt_i32_e32 vcc, v7, v8
	v_add3_u32 v93, 0, v6, v0
	v_lshlrev_b32_e32 v0, 4, v4
	v_lshlrev_b32_e32 v74, 3, v5
	v_lshl_add_u32 v89, v5, 5, 0
	v_cndmask_b32_e32 v7, v216, v7, vcc
	v_cmp_eq_u32_e32 vcc, 0, v5
	v_mul_lo_u32 v94, v88, s30
	v_lshl_add_u64 v[4:5], s[56:57], 0, v[0:1]
	v_lshlrev_b64 v[2:3], 1, v[2:3]
	v_lshlrev_b32_e32 v92, 2, v7
	v_add_u32_e32 v6, 0x10400, v94
	v_add_u32_e32 v7, 0x14500, v94
	v_add_u32_e32 v8, 0x18600, v94
	v_add_u32_e32 v9, 0x1c700, v94
	v_lshl_add_u64 v[4:5], v[4:5], 0, v[2:3]
	v_or_b32_e32 v2, v2, v0
	v_readlane_b32 s6, v254, 39
	v_lshl_add_u64 v[76:77], s[0:1], 0, v[4:5]
	v_lshl_add_u64 v[78:79], s[0:1], 0, v[2:3]
	v_or_b32_e32 v95, 0x2000, v75
	s_lshl_b32 s2, s6, 6
	v_add_u32_e32 v96, v89, v6
	v_add_u32_e32 v97, v89, v7
	v_add_u32_e32 v98, v89, v8
	v_add_u32_e32 v99, v89, v9
	s_mov_b32 s3, s59
	s_cmpk_lg_i32 s92, 0x100
	s_cbranch_scc1 .Lsmp_map_keep67
	s_and_b32 s4, s6, 7
	s_lshr_b32 s5, s6, 3
	s_lshl_b32 s4, s4, 2
	s_lshr_b32 s2, s5, 3
	s_add_i32 s4, s4, s2
	s_and_b32 s5, s5, 7
	s_lshl_b32 s4, s4, 3
	s_or_b32 s6, s4, s5
	s_lshl_b32 s2, s6, 6
	s_lshl_b32 s3, s6, 3
.Lsmp_map_keep67:
	s_branch .LBB0_67

; template <bool GATE>
; __device__ __forceinline__ void sample_gemm_res(LAS unsigned char* lds, const bf16* Amat, const bf16* Bt, const bf16* Hin, bf16* Hout, float* rss_out, const bf16* PP, const float* rss_in, int bid, int tid) {
;     const int wave = tid >> 6, lane = tid & 63, lr = lane & 15, kg = lane >> 4;
;   for (int tile = bid; tile < 256; tile += (int)gridDim.x) {
;     const int m0 = TP + (tile & 7) * 64, n0 = (tile >> 3) * 64;
;     const bf16x8* ap = (const bf16x8*)(Amat + (size_t)(m0 + lr) * 2048 + wave * 256 + 8 * kg);
;     const bf16x8* bp = (const bf16x8*)(Bt + (size_t)(n0 + lr) * 2048 + wave * 256 + 8 * kg);
;     const int erow = m0 + (tid >> 3); const size_t ep = (size_t)erow * 2048 + n0 + (tid & 7) * 8;
;     const u32x4 hw = *(const u32x4*)(Hin + ep); u32x4 pw = (u32x4){0u, 0u, 0u, 0u}; float rsi = 0.f; if (GATE) { pw = *(const u32x4*)(PP + ep); rsi = rss_in[erow]; }
;     ...
;       sq += __shfl_xor(sq, 1); sq += __shfl_xor(sq, 2); sq += __shfl_xor(sq, 4);
.LBB0_112:
	v_mov_b32_e32 v0, v183
	s_and_b64 vcc, exec, s[40:41]
	s_cbranch_vccnz .LBB0_119
	v_and_b32_e32 v8, 64, v216
	v_xor_b32_e32 v7, 1, v216
	v_add_u32_e32 v8, 64, v8
	v_cmp_lt_i32_e32 vcc, v7, v8
	s_waitcnt vmcnt(0)
	v_and_b32_e32 v71, 15, v0
	v_bfe_u32 v4, v0, 4, 2
	v_cndmask_b32_e32 v7, v216, v7, vcc
	v_lshlrev_b32_e32 v86, 2, v7
	v_xor_b32_e32 v7, 2, v216
	v_lshlrev_b32_e32 v2, 2, v0
	v_ashrrev_i32_e32 v84, 3, v0
	v_and_b32_e32 v5, 7, v0
	v_and_b32_e32 v0, 0x3fffffc0, v0
	v_cmp_lt_i32_e32 vcc, v7, v8
	v_lshl_or_b32 v0, v4, 2, v0
	v_lshlrev_b32_e32 v6, 2, v71
	v_cndmask_b32_e32 v7, v216, v7, vcc
	v_lshlrev_b32_e32 v87, 2, v7
	v_xor_b32_e32 v7, 4, v216
	v_mul_lo_u32 v0, v0, s30
	s_add_u32 s0, s14, s52
	v_cmp_lt_i32_e32 vcc, v7, v8
	v_add3_u32 v89, 0, v6, v0
	s_addc_u32 s1, 0, s53
	v_lshlrev_b32_e32 v0, 4, v4
	v_lshlrev_b32_e32 v70, 3, v5
	v_lshl_add_u32 v85, v5, 5, 0
	v_cndmask_b32_e32 v7, v216, v7, vcc
	v_cmp_eq_u32_e32 vcc, 0, v5
	v_lshl_add_u64 v[4:5], s[0:1], 0, v[0:1]
	s_load_dwordx2 s[0:1], s[60:61], 0x148
	v_and_b32_e32 v2, 0xffffff00, v2
	s_waitcnt lgkmcnt(0)
	v_ashrrev_i32_e32 v3, 31, v2
	v_mul_lo_u32 v90, v84, s30
	v_lshlrev_b64 v[2:3], 1, v[2:3]
	v_lshlrev_b32_e32 v88, 2, v7
	v_add_u32_e32 v6, 0x10400, v90
	v_add_u32_e32 v7, 0x14500, v90
	v_add_u32_e32 v8, 0x18600, v90
	v_add_u32_e32 v9, 0x1c700, v90
	v_lshl_add_u64 v[4:5], v[4:5], 0, v[2:3]
	v_or_b32_e32 v2, v2, v0
	v_readlane_b32 s6, v254, 39
	v_lshl_add_u64 v[72:73], s[0:1], 0, v[4:5]
	v_lshl_add_u64 v[74:75], s[0:1], 0, v[2:3]
	v_or_b32_e32 v91, 0x2000, v71
	s_lshl_b32 s2, s6, 6
	v_add_u32_e32 v92, v85, v6
	v_add_u32_e32 v93, v85, v7
	v_add_u32_e32 v94, v85, v8
	v_add_u32_e32 v95, v85, v9
	s_mov_b32 s3, s59
	s_cmpk_lg_i32 s92, 0x100
	s_cbranch_scc1 .Lsmp_map_keep115
	s_and_b32 s4, s6, 7
	s_lshr_b32 s5, s6, 3
	s_lshl_b32 s4, s4, 2
	s_lshr_b32 s2, s5, 3
	s_add_i32 s4, s4, s2
	s_and_b32 s5, s5, 7
	s_lshl_b32 s4, s4, 3
	s_or_b32 s6, s4, s5
	s_lshl_b32 s2, s6, 6
	s_lshl_b32 s3, s6, 3
